# FoX attention phase: one static s_setprio 1 for waves 4-7 (reset at phase exit), on top of early-invalidate seams
# baseline (speedup 1.0000x reference)
.LBB0_322:
	v_readlane_b32 s0, v236, 4
	s_cmp_lt_i32 s0, 3
	s_cselect_b64 s[10:11], -1, 0
	s_or_b32 s0, s5, s16
	v_readlane_b32 s1, v236, 5
	v_writelane_b32 v236, s0, 8
	s_ashr_i32 s84, s2, 6
	s_and_b64 s[14:15], s[10:11], s[14:15]
	s_cmpk_lt_i32 s87, 0x400
	v_readlane_b32 s6, v236, 6
	s_cselect_b64 s[0:1], -1, 0
	v_readlane_b32 s7, v236, 7
	s_or_b64 s[0:1], s[6:7], s[0:1]
	s_and_b64 s[0:1], s[14:15], s[0:1]
	s_andn2_b64 vcc, exec, s[0:1]
	s_cbranch_vccnz .LBB0_456
	s_lshr_b32 s0, s4, 1
	s_and_b32 s3, s0, 16
	s_lshl_b32 s0, s84, 2
	s_add_i32 s3, s3, s0
	v_readlane_b32 s0, v236, 8
	s_waitcnt lgkmcnt(0)
	s_and_b32 s38, s0, 31
	s_add_u32 s39, s70, 0x2000000
	s_addc_u32 s40, s71, 0
	s_add_u32 s41, s72, 0xd800000
	s_addc_u32 s42, s73, 0
	s_add_u32 s43, s72, 0x400000
	v_mbcnt_lo_u32_b32 v1, -1, 0
	s_addc_u32 s44, s73, 0
	v_mbcnt_hi_u32_b32 v1, -1, v1
	s_add_u32 s45, s72, 0x80000
	v_and_b32_e32 v2, 64, v1
	s_mov_b32 s18, 0x652b82fe
	s_addc_u32 s52, s73, 0
	s_mov_b32 s17, 0
	v_mov_b32_e32 v101, 0
	v_add_u32_e32 v122, 64, v2
	v_xor_b32_e32 v123, 1, v1
	v_xor_b32_e32 v124, 2, v1
	v_xor_b32_e32 v125, 4, v1
	v_xor_b32_e32 v126, 8, v1
	v_xor_b32_e32 v127, 16, v1
	s_mov_b32 s53, 0xf800000
	v_mov_b32_e32 v128, 0x260
	v_mov_b32_e32 v129, 0x3a83126f
	s_mov_b32 s19, 0x3ff71547
	s_add_i32 s54, 0, 0xc800
	s_mov_b64 s[20:21], 0x1000
	s_mov_b64 s[24:25], 0x20000
	s_mov_b32 s55, 0x42c80000
	s_movk_i32 s58, 0xc0
	s_mov_b64 s[26:27], 0x40000
	s_movk_i32 s59, 0x60
	s_mov_b32 s60, 0x41000000
	s_add_i32 s61, 0, 0xc900
	v_mov_b32_e32 v130, 0xff800000
	s_mov_b32 s63, 0
	s_mov_b32 s62, s87
	v_readfirstlane_b32 s0, v182
	s_lshr_b32 s0, s0, 8
	s_cmp_lg_u32 s0, 0
	s_cbranch_scc0 .Lfox_prio_skip
	s_setprio 1
.Lfox_prio_skip:
	s_branch .LBB0_325
.LBB0_324:
	s_or_b64 exec, exec, s[6:7]
	s_add_i32 s4, s63, 1
	s_add_i32 s62, s62, s92
	s_cmp_lt_u32 s63, 3
	s_cselect_b64 s[0:1], -1, 0
	s_cmpk_lt_i32 s62, 0x400
	v_cndmask_b32_e64 v2, 0, 1, s[0:1]
	s_cselect_b64 s[0:1], -1, 0
	s_waitcnt lgkmcnt(0)
	v_cndmask_b32_e64 v3, 0, 1, s[0:1]
	v_readlane_b32 s0, v236, 6
	v_readlane_b32 s1, v236, 7
	s_mov_b32 s63, s4
	s_nop 0
	v_cndmask_b32_e64 v2, v3, v2, s[0:1]
	v_and_b32_e32 v2, 1, v2
	v_cmp_eq_u32_e32 vcc, 1, v2
	s_barrier
	s_cbranch_vccz .LBB0_456

.LBB0_456:
	s_setprio 0
	s_xor_b64 s[0:1], s[12:13], -1
	v_writelane_b32 v236, s0, 9
	s_nop 1
	v_writelane_b32 v236, s1, 10
	s_nop 0
	v_readlane_b32 s4, v236, 4
	v_readlane_b32 s5, v236, 5
	s_cmp_gt_i32 s5, 3
	s_cselect_b64 s[6:7], -1, 0
	s_and_b64 s[0:1], s[14:15], s[6:7]
	s_andn2_b64 vcc, exec, s[0:1]
	s_cbranch_vccnz .LBB0_518
	s_mov_b64 s[0:1], -1
	s_and_b64 vcc, exec, s[78:79]
	s_cbranch_vccz .LBB0_511
	s_waitcnt vmcnt(0)
	s_waitcnt lgkmcnt(0)
	s_barrier
	s_and_saveexec_b64 s[0:1], s[22:23]
	s_cbranch_execz .LBB0_510
	s_add_i32 s3, 0, 0x20160
	v_mov_b32_e32 v1, s3
	s_waitcnt vmcnt(0) expcnt(0) lgkmcnt(0)
	ds_read_b32 v3, v1
	s_add_i32 s3, 0, 0x20164
	v_mov_b32_e32 v1, s3
	ds_read_b32 v1, v1
	s_waitcnt lgkmcnt(1)
	v_cmp_ne_u32_e32 vcc, 0, v3
	s_cbranch_vccnz .LBB0_474
	s_add_u32 s8, s72, 0x4200
	s_addc_u32 s9, s73, 0
	s_add_u32 s12, s72, 0x4400
	s_addc_u32 s13, s73, 0
	s_add_u32 s14, s72, 0x4500
	s_addc_u32 s15, s73, 0
	s_add_u32 s16, s72, 0x4600
	s_addc_u32 s17, s73, 0
	s_add_u32 s18, s72, 0x4700
	s_addc_u32 s19, s73, 0
	s_add_u32 s20, s72, 0x4800
	s_addc_u32 s21, s73, 0
	s_add_u32 s24, s72, 0x4900
	s_addc_u32 s25, s73, 0
	s_add_u32 s26, s72, 0x4a00
	s_addc_u32 s27, s73, 0
	s_add_u32 s28, s72, 0x4b00
	s_addc_u32 s29, s73, 0
	s_add_u32 s30, s72, 0x4c00
	s_addc_u32 s31, s73, 0
	s_add_u32 s34, s72, 0x4d00
	s_addc_u32 s35, s73, 0
	s_add_u32 s36, s72, 0x4e00
	s_addc_u32 s37, s73, 0
	s_add_u32 s38, s72, 0x4f00
	s_addc_u32 s39, s73, 0
	s_add_u32 s40, s72, 0x5000
	s_addc_u32 s41, s73, 0
	s_add_u32 s42, s72, 0x5100
	s_addc_u32 s43, s73, 0
	s_add_u32 s44, s72, 0x5200
	s_addc_u32 s45, s73, 0
	s_mul_i32 s3, s93, s97
	s_add_u32 s52, s72, 0x5300
	s_mul_i32 s3, s3, s92
	s_addc_u32 s53, s73, 0
	s_mov_b32 s4, 1
	v_mov_b32_e32 v17, 0
	s_branch .LBB0_462
